# v16: out epilogue residual loads requested before the gate-value wait
# speedup vs baseline: 1.0486x; 1.0012x over previous
.LBB0_14:
	v_ashrrev_i32_e32 v0, 12, v0
	v_add_u32_e32 v0, 1, v0
	v_cndmask_b32_e64 v0, v0, 0, s[8:9]
	s_load_dwordx2 s[8:9], s[0:1], 0xe8
	s_mul_i32 s10, s74, 9
	v_add_u32_e32 v0, s10, v0
	v_mov_b32_e32 v121, v1
	v_mov_b32_e32 v123, v1
	s_waitcnt lgkmcnt(0)
	v_lshl_add_u64 v[68:69], s[8:9], 0, v[70:71]
	s_load_dwordx2 s[8:9], s[0:1], 0x188
	s_mov_b64 s[24:25], -1
	s_waitcnt lgkmcnt(0)
	v_mov_b64_e32 v[70:71], s[8:9]
	v_mad_i64_i32 v[70:71], s[8:9], v0, s87, v[70:71]
	v_lshl_add_u64 v[70:71], s[22:23], 2, v[70:71]
	v_lshl_add_u64 v[70:71], v[70:71], 0, v[120:121]
	v_lshl_add_u64 v[70:71], v[70:71], 0, v[122:123]
	s_mov_b64 s[8:9], 0x2000
	v_lshl_add_u64 v[72:73], v[70:71], 0, s[8:9]
	s_movk_i32 s8, 0x2000
	v_add_co_u32_e32 v70, vcc, s8, v70
	s_nop 1
	v_addc_co_u32_e32 v71, vcc, 0, v71, vcc
	global_load_dword v0, v[70:71], off
	s_nop 0
	global_load_dword v72, v[72:73], off offset:64
	v_mov_b32_e32 v71, s23
	v_or_b32_e32 v70, s22, v86
	s_and_b64 vcc, exec, s[20:21]
	v_lshl_add_u64 v[152:153], v[70:71], 0, v[88:89]
	v_lshlrev_b64 v[152:153], 2, v[152:153]
	v_lshl_add_u64 v[152:153], v[66:67], 0, v[152:153]
	global_load_dwordx4 v[152:155], v[152:153], off
	v_lshl_add_u64 v[156:157], v[70:71], 0, v[90:91]
	v_lshlrev_b64 v[156:157], 2, v[156:157]
	v_lshl_add_u64 v[156:157], v[66:67], 0, v[156:157]
	global_load_dwordx4 v[156:159], v[156:157], off
	v_lshl_add_u64 v[160:161], v[70:71], 0, v[92:93]
	v_lshlrev_b64 v[160:161], 2, v[160:161]
	v_lshl_add_u64 v[160:161], v[66:67], 0, v[160:161]
	global_load_dwordx4 v[160:163], v[160:161], off
	v_lshl_add_u64 v[164:165], v[70:71], 0, v[94:95]
	v_lshlrev_b64 v[164:165], 2, v[164:165]
	v_lshl_add_u64 v[164:165], v[66:67], 0, v[164:165]
	global_load_dwordx4 v[164:167], v[164:165], off
	v_lshl_add_u64 v[168:169], v[70:71], 0, v[96:97]
	v_lshlrev_b64 v[168:169], 2, v[168:169]
	v_lshl_add_u64 v[168:169], v[66:67], 0, v[168:169]
	global_load_dwordx4 v[168:171], v[168:169], off
	v_lshl_add_u64 v[172:173], v[70:71], 0, v[98:99]
	v_lshlrev_b64 v[172:173], 2, v[172:173]
	v_lshl_add_u64 v[172:173], v[66:67], 0, v[172:173]
	global_load_dwordx4 v[172:175], v[172:173], off
	v_lshl_add_u64 v[176:177], v[70:71], 0, v[100:101]
	v_lshlrev_b64 v[176:177], 2, v[176:177]
	v_lshl_add_u64 v[176:177], v[66:67], 0, v[176:177]
	global_load_dwordx4 v[176:179], v[176:177], off
	v_lshl_add_u64 v[180:181], v[70:71], 0, v[102:103]
	v_lshlrev_b64 v[180:181], 2, v[180:181]
	v_lshl_add_u64 v[180:181], v[66:67], 0, v[180:181]
	global_load_dwordx4 v[180:183], v[180:181], off
	v_lshl_add_u64 v[184:185], v[70:71], 0, v[104:105]
	v_lshlrev_b64 v[184:185], 2, v[184:185]
	v_lshl_add_u64 v[184:185], v[66:67], 0, v[184:185]
	global_load_dwordx4 v[184:187], v[184:185], off
	v_lshl_add_u64 v[188:189], v[70:71], 0, v[106:107]
	v_lshlrev_b64 v[188:189], 2, v[188:189]
	v_lshl_add_u64 v[188:189], v[66:67], 0, v[188:189]
	global_load_dwordx4 v[188:191], v[188:189], off
	v_lshl_add_u64 v[192:193], v[70:71], 0, v[108:109]
	v_lshlrev_b64 v[192:193], 2, v[192:193]
	v_lshl_add_u64 v[192:193], v[66:67], 0, v[192:193]
	global_load_dwordx4 v[192:195], v[192:193], off
	v_lshl_add_u64 v[196:197], v[70:71], 0, v[110:111]
	v_lshlrev_b64 v[196:197], 2, v[196:197]
	v_lshl_add_u64 v[196:197], v[66:67], 0, v[196:197]
	global_load_dwordx4 v[196:199], v[196:197], off
	v_lshl_add_u64 v[200:201], v[70:71], 0, v[112:113]
	v_lshlrev_b64 v[200:201], 2, v[200:201]
	v_lshl_add_u64 v[200:201], v[66:67], 0, v[200:201]
	global_load_dwordx4 v[200:203], v[200:201], off
	v_lshl_add_u64 v[204:205], v[70:71], 0, v[114:115]
	v_lshlrev_b64 v[204:205], 2, v[204:205]
	v_lshl_add_u64 v[204:205], v[66:67], 0, v[204:205]
	global_load_dwordx4 v[204:207], v[204:205], off
	v_lshl_add_u64 v[208:209], v[70:71], 0, v[116:117]
	v_lshlrev_b64 v[208:209], 2, v[208:209]
	v_lshl_add_u64 v[208:209], v[66:67], 0, v[208:209]
	global_load_dwordx4 v[208:211], v[208:209], off
	v_lshl_add_u64 v[74:75], v[70:71], 0, v[118:119]
	v_lshlrev_b64 v[74:75], 2, v[74:75]
	v_lshl_add_u64 v[74:75], v[66:67], 0, v[74:75]
	global_load_dwordx4 v[74:77], v[74:75], off
	s_waitcnt vmcnt(16)
	v_mul_f32_e32 v62, v62, v0
	v_mul_f32_e32 v58, v58, v72
	ds_write2_b32 v136, v62, v58 offset1:16
	v_mul_f32_e32 v58, v63, v0
	v_mul_f32_e32 v59, v59, v72
	ds_write2_b32 v136, v58, v59 offset0:36 offset1:52
	v_mul_f32_e32 v58, v64, v0
	v_mul_f32_e32 v59, v60, v72
	ds_write2_b32 v136, v58, v59 offset0:72 offset1:88
	v_mul_f32_e32 v58, v65, v0
	v_mul_f32_e32 v59, v61, v72
	ds_write2_b32 v136, v58, v59 offset0:108 offset1:124
	v_mul_f32_e32 v54, v54, v0
	v_mul_f32_e32 v58, v50, v72
	v_add_u32_e32 v50, 0x800, v136
	ds_write2_b32 v50, v54, v58 offset0:64 offset1:80
	v_mul_f32_e32 v54, v55, v0
	v_mul_f32_e32 v51, v51, v72
	ds_write2_b32 v50, v54, v51 offset0:100 offset1:116
	v_mul_f32_e32 v51, v56, v0
	v_mul_f32_e32 v52, v52, v72
	ds_write2_b32 v50, v51, v52 offset0:136 offset1:152
	v_mul_f32_e32 v51, v57, v0
	v_mul_f32_e32 v52, v53, v72
	v_lshl_add_u64 v[56:57], v[70:71], 0, v[88:89]
	ds_write2_b32 v50, v51, v52 offset0:172 offset1:188
	v_lshlrev_b64 v[60:61], 2, v[56:57]
	s_waitcnt lgkmcnt(0)
	v_lshl_add_u64 v[56:57], v[66:67], 0, v[60:61]
	ds_read_b128 v[52:55], v137
	v_mul_f32_e32 v46, v46, v0
	v_mul_f32_e32 v42, v42, v72
	v_mul_f32_e32 v38, v38, v0
	v_mul_f32_e32 v34, v34, v72
	v_mul_f32_e32 v43, v43, v72
	v_mul_f32_e32 v35, v35, v72
	v_mul_f32_e32 v30, v30, v0
	v_mul_f32_e32 v26, v26, v72
	v_mul_f32_e32 v22, v22, v0
	v_mul_f32_e32 v18, v18, v72
	v_mul_f32_e32 v27, v27, v72
	v_mul_f32_e32 v19, v19, v72
	v_mul_f32_e32 v14, v14, v0
	v_mul_f32_e32 v10, v10, v72
	v_mul_f32_e32 v6, v6, v0
	v_mul_f32_e32 v2, v2, v72
	v_mul_f32_e32 v11, v11, v72
	v_mul_f32_e32 v3, v3, v72
	s_waitcnt vmcnt(15) lgkmcnt(0)
	v_pk_fma_f32 v[54:55], v[154:155], s[98:99], v[54:55] op_sel_hi:[1,0,1]
	v_pk_fma_f32 v[52:53], v[152:153], s[98:99], v[52:53] op_sel_hi:[1,0,1]
	v_lshl_add_u64 v[56:57], v[68:69], 0, v[60:61]
	global_store_dwordx4 v[56:57], v[52:55], off sc0 sc1
	v_lshl_add_u64 v[56:57], v[70:71], 0, v[90:91]
	v_lshlrev_b64 v[60:61], 2, v[56:57]
	v_lshl_add_u64 v[56:57], v[66:67], 0, v[60:61]
	ds_read_b128 v[52:55], v138
	s_waitcnt vmcnt(15) lgkmcnt(0)
	v_pk_fma_f32 v[54:55], v[158:159], s[98:99], v[54:55] op_sel_hi:[1,0,1]
	v_pk_fma_f32 v[52:53], v[156:157], s[98:99], v[52:53] op_sel_hi:[1,0,1]
	v_lshl_add_u64 v[56:57], v[68:69], 0, v[60:61]
	global_store_dwordx4 v[56:57], v[52:55], off sc0 sc1
	v_lshl_add_u64 v[56:57], v[70:71], 0, v[92:93]
	v_lshlrev_b64 v[60:61], 2, v[56:57]
	v_lshl_add_u64 v[56:57], v[66:67], 0, v[60:61]
	ds_read_b128 v[52:55], v139
	s_waitcnt vmcnt(15) lgkmcnt(0)
	v_pk_fma_f32 v[54:55], v[162:163], s[98:99], v[54:55] op_sel_hi:[1,0,1]
	v_pk_fma_f32 v[52:53], v[160:161], s[98:99], v[52:53] op_sel_hi:[1,0,1]
	v_lshl_add_u64 v[56:57], v[68:69], 0, v[60:61]
	global_store_dwordx4 v[56:57], v[52:55], off sc0 sc1
	v_lshl_add_u64 v[56:57], v[70:71], 0, v[94:95]
	v_lshlrev_b64 v[60:61], 2, v[56:57]
	v_lshl_add_u64 v[56:57], v[66:67], 0, v[60:61]
	ds_read_b128 v[52:55], v140
	s_waitcnt vmcnt(15) lgkmcnt(0)
	v_pk_fma_f32 v[54:55], v[166:167], s[98:99], v[54:55] op_sel_hi:[1,0,1]
	v_pk_fma_f32 v[52:53], v[164:165], s[98:99], v[52:53] op_sel_hi:[1,0,1]
	v_lshl_add_u64 v[56:57], v[68:69], 0, v[60:61]
	global_store_dwordx4 v[56:57], v[52:55], off sc0 sc1
	s_waitcnt lgkmcnt(0)
	ds_write2_b32 v136, v46, v42 offset1:16
	v_mul_f32_e32 v42, v47, v0
	ds_write2_b32 v50, v38, v34 offset0:64 offset1:80
	v_mul_f32_e32 v34, v39, v0
	ds_write2_b32 v136, v42, v43 offset0:36 offset1:52
	v_mul_f32_e32 v42, v48, v0
	v_mul_f32_e32 v43, v44, v72
	ds_write2_b32 v50, v34, v35 offset0:100 offset1:116
	v_mul_f32_e32 v34, v40, v0
	v_mul_f32_e32 v35, v36, v72
	ds_write2_b32 v136, v42, v43 offset0:72 offset1:88
	v_mul_f32_e32 v42, v49, v0
	v_mul_f32_e32 v43, v45, v72
	ds_write2_b32 v50, v34, v35 offset0:136 offset1:152
	v_mul_f32_e32 v34, v41, v0
	v_mul_f32_e32 v35, v37, v72
	v_lshl_add_u64 v[38:39], v[70:71], 0, v[96:97]
	ds_write2_b32 v136, v42, v43 offset0:108 offset1:124
	ds_write2_b32 v50, v34, v35 offset0:172 offset1:188
	v_lshlrev_b64 v[42:43], 2, v[38:39]
	s_waitcnt lgkmcnt(0)
	v_lshl_add_u64 v[38:39], v[66:67], 0, v[42:43]
	ds_read_b128 v[34:37], v137
	s_waitcnt vmcnt(15) lgkmcnt(0)
	v_pk_fma_f32 v[36:37], v[170:171], s[98:99], v[36:37] op_sel_hi:[1,0,1]
	v_pk_fma_f32 v[34:35], v[168:169], s[98:99], v[34:35] op_sel_hi:[1,0,1]
	v_lshl_add_u64 v[38:39], v[68:69], 0, v[42:43]
	global_store_dwordx4 v[38:39], v[34:37], off sc0 sc1
	v_lshl_add_u64 v[38:39], v[70:71], 0, v[98:99]
	v_lshlrev_b64 v[42:43], 2, v[38:39]
	v_lshl_add_u64 v[38:39], v[66:67], 0, v[42:43]
	ds_read_b128 v[34:37], v138
	s_waitcnt vmcnt(15) lgkmcnt(0)
	v_pk_fma_f32 v[36:37], v[174:175], s[98:99], v[36:37] op_sel_hi:[1,0,1]
	v_pk_fma_f32 v[34:35], v[172:173], s[98:99], v[34:35] op_sel_hi:[1,0,1]
	v_lshl_add_u64 v[38:39], v[68:69], 0, v[42:43]
	global_store_dwordx4 v[38:39], v[34:37], off sc0 sc1
	v_lshl_add_u64 v[38:39], v[70:71], 0, v[100:101]
	v_lshlrev_b64 v[42:43], 2, v[38:39]
	v_lshl_add_u64 v[38:39], v[66:67], 0, v[42:43]
	ds_read_b128 v[34:37], v139
	s_waitcnt vmcnt(15) lgkmcnt(0)
	v_pk_fma_f32 v[36:37], v[178:179], s[98:99], v[36:37] op_sel_hi:[1,0,1]
	v_pk_fma_f32 v[34:35], v[176:177], s[98:99], v[34:35] op_sel_hi:[1,0,1]
	v_lshl_add_u64 v[38:39], v[68:69], 0, v[42:43]
	global_store_dwordx4 v[38:39], v[34:37], off sc0 sc1
	v_lshl_add_u64 v[38:39], v[70:71], 0, v[102:103]
	v_lshlrev_b64 v[42:43], 2, v[38:39]
	v_lshl_add_u64 v[38:39], v[66:67], 0, v[42:43]
	ds_read_b128 v[34:37], v140
	s_waitcnt vmcnt(15) lgkmcnt(0)
	v_pk_fma_f32 v[36:37], v[182:183], s[98:99], v[36:37] op_sel_hi:[1,0,1]
	v_pk_fma_f32 v[34:35], v[180:181], s[98:99], v[34:35] op_sel_hi:[1,0,1]
	v_lshl_add_u64 v[38:39], v[68:69], 0, v[42:43]
	global_store_dwordx4 v[38:39], v[34:37], off sc0 sc1
	s_waitcnt lgkmcnt(0)
	ds_write2_b32 v136, v30, v26 offset1:16
	v_mul_f32_e32 v26, v31, v0
	ds_write2_b32 v50, v22, v18 offset0:64 offset1:80
	v_mul_f32_e32 v18, v23, v0
	ds_write2_b32 v136, v26, v27 offset0:36 offset1:52
	v_mul_f32_e32 v26, v32, v0
	v_mul_f32_e32 v27, v28, v72
	ds_write2_b32 v50, v18, v19 offset0:100 offset1:116
	v_mul_f32_e32 v18, v24, v0
	v_mul_f32_e32 v19, v20, v72
	ds_write2_b32 v136, v26, v27 offset0:72 offset1:88
	v_mul_f32_e32 v26, v33, v0
	v_mul_f32_e32 v27, v29, v72
	ds_write2_b32 v50, v18, v19 offset0:136 offset1:152
	v_mul_f32_e32 v18, v25, v0
	v_mul_f32_e32 v19, v21, v72
	v_lshl_add_u64 v[22:23], v[70:71], 0, v[104:105]
	ds_write2_b32 v136, v26, v27 offset0:108 offset1:124
	ds_write2_b32 v50, v18, v19 offset0:172 offset1:188
	v_lshlrev_b64 v[26:27], 2, v[22:23]
	s_waitcnt lgkmcnt(0)
	v_lshl_add_u64 v[22:23], v[66:67], 0, v[26:27]
	ds_read_b128 v[18:21], v137
	s_waitcnt vmcnt(15) lgkmcnt(0)
	v_pk_fma_f32 v[20:21], v[186:187], s[98:99], v[20:21] op_sel_hi:[1,0,1]
	v_pk_fma_f32 v[18:19], v[184:185], s[98:99], v[18:19] op_sel_hi:[1,0,1]
	v_lshl_add_u64 v[22:23], v[68:69], 0, v[26:27]
	global_store_dwordx4 v[22:23], v[18:21], off sc0 sc1
	v_lshl_add_u64 v[22:23], v[70:71], 0, v[106:107]
	v_lshlrev_b64 v[26:27], 2, v[22:23]
	v_lshl_add_u64 v[22:23], v[66:67], 0, v[26:27]
	ds_read_b128 v[18:21], v138
	s_waitcnt vmcnt(15) lgkmcnt(0)
	v_pk_fma_f32 v[20:21], v[190:191], s[98:99], v[20:21] op_sel_hi:[1,0,1]
	v_pk_fma_f32 v[18:19], v[188:189], s[98:99], v[18:19] op_sel_hi:[1,0,1]
	v_lshl_add_u64 v[22:23], v[68:69], 0, v[26:27]
	global_store_dwordx4 v[22:23], v[18:21], off sc0 sc1
	v_lshl_add_u64 v[22:23], v[70:71], 0, v[108:109]
	v_lshlrev_b64 v[26:27], 2, v[22:23]
	v_lshl_add_u64 v[22:23], v[66:67], 0, v[26:27]
	ds_read_b128 v[18:21], v139
	s_waitcnt vmcnt(15) lgkmcnt(0)
	v_pk_fma_f32 v[20:21], v[194:195], s[98:99], v[20:21] op_sel_hi:[1,0,1]
	v_pk_fma_f32 v[18:19], v[192:193], s[98:99], v[18:19] op_sel_hi:[1,0,1]
	v_lshl_add_u64 v[22:23], v[68:69], 0, v[26:27]
	global_store_dwordx4 v[22:23], v[18:21], off sc0 sc1
	v_lshl_add_u64 v[22:23], v[70:71], 0, v[110:111]
	v_lshlrev_b64 v[26:27], 2, v[22:23]
	v_lshl_add_u64 v[22:23], v[66:67], 0, v[26:27]
	ds_read_b128 v[18:21], v140
	s_waitcnt vmcnt(15) lgkmcnt(0)
	v_pk_fma_f32 v[20:21], v[198:199], s[98:99], v[20:21] op_sel_hi:[1,0,1]
	v_pk_fma_f32 v[18:19], v[196:197], s[98:99], v[18:19] op_sel_hi:[1,0,1]
	v_lshl_add_u64 v[22:23], v[68:69], 0, v[26:27]
	global_store_dwordx4 v[22:23], v[18:21], off sc0 sc1
	s_waitcnt lgkmcnt(0)
	ds_write2_b32 v136, v14, v10 offset1:16
	v_mul_f32_e32 v10, v15, v0
	ds_write2_b32 v50, v6, v2 offset0:64 offset1:80
	v_mul_f32_e32 v2, v7, v0
	ds_write2_b32 v136, v10, v11 offset0:36 offset1:52
	v_mul_f32_e32 v10, v16, v0
	v_mul_f32_e32 v11, v12, v72
	ds_write2_b32 v50, v2, v3 offset0:100 offset1:116
	v_mul_f32_e32 v2, v8, v0
	v_mul_f32_e32 v3, v4, v72
	ds_write2_b32 v136, v10, v11 offset0:72 offset1:88
	v_mul_f32_e32 v10, v17, v0
	v_mul_f32_e32 v11, v13, v72
	ds_write2_b32 v50, v2, v3 offset0:136 offset1:152
	v_mul_f32_e32 v0, v9, v0
	v_mul_f32_e32 v2, v5, v72
	v_lshl_add_u64 v[6:7], v[70:71], 0, v[112:113]
	ds_write2_b32 v136, v10, v11 offset0:108 offset1:124
	ds_write2_b32 v50, v0, v2 offset0:172 offset1:188
	v_lshlrev_b64 v[10:11], 2, v[6:7]
	s_waitcnt lgkmcnt(0)
	v_lshl_add_u64 v[6:7], v[66:67], 0, v[10:11]
	ds_read_b128 v[2:5], v137
	s_waitcnt vmcnt(15) lgkmcnt(0)
	v_pk_fma_f32 v[4:5], v[202:203], s[98:99], v[4:5] op_sel_hi:[1,0,1]
	v_pk_fma_f32 v[2:3], v[200:201], s[98:99], v[2:3] op_sel_hi:[1,0,1]
	v_lshl_add_u64 v[6:7], v[68:69], 0, v[10:11]
	global_store_dwordx4 v[6:7], v[2:5], off sc0 sc1
	v_lshl_add_u64 v[6:7], v[70:71], 0, v[114:115]
	v_lshlrev_b64 v[10:11], 2, v[6:7]
	v_lshl_add_u64 v[6:7], v[66:67], 0, v[10:11]
	ds_read_b128 v[2:5], v138
	s_waitcnt vmcnt(15) lgkmcnt(0)
	v_pk_fma_f32 v[4:5], v[206:207], s[98:99], v[4:5] op_sel_hi:[1,0,1]
	v_pk_fma_f32 v[2:3], v[204:205], s[98:99], v[2:3] op_sel_hi:[1,0,1]
	v_lshl_add_u64 v[6:7], v[68:69], 0, v[10:11]
	global_store_dwordx4 v[6:7], v[2:5], off sc0 sc1
	v_lshl_add_u64 v[6:7], v[70:71], 0, v[116:117]
	v_lshlrev_b64 v[10:11], 2, v[6:7]
	v_lshl_add_u64 v[6:7], v[66:67], 0, v[10:11]
	ds_read_b128 v[2:5], v139
	s_waitcnt vmcnt(15) lgkmcnt(0)
	v_pk_fma_f32 v[4:5], v[210:211], s[98:99], v[4:5] op_sel_hi:[1,0,1]
	v_pk_fma_f32 v[2:3], v[208:209], s[98:99], v[2:3] op_sel_hi:[1,0,1]
	v_lshl_add_u64 v[6:7], v[68:69], 0, v[10:11]
	global_store_dwordx4 v[6:7], v[2:5], off sc0 sc1
	v_lshl_add_u64 v[6:7], v[70:71], 0, v[118:119]
	v_lshlrev_b64 v[10:11], 2, v[6:7]
	v_lshl_add_u64 v[6:7], v[66:67], 0, v[10:11]
	ds_read_b128 v[2:5], v140
	s_waitcnt vmcnt(15) lgkmcnt(0)
	v_pk_fma_f32 v[4:5], v[76:77], s[98:99], v[4:5] op_sel_hi:[1,0,1]
	v_pk_fma_f32 v[2:3], v[74:75], s[98:99], v[2:3] op_sel_hi:[1,0,1]
	v_lshl_add_u64 v[6:7], v[68:69], 0, v[10:11]
	global_store_dwordx4 v[6:7], v[2:5], off sc0 sc1
	s_waitcnt lgkmcnt(0)
	s_cbranch_vccnz .LBB0_45
